# DIFF attention: cross-half row-max exchange done with v_permlane32_swap (VALU) instead of ds_bpermute + LDS round trip, on top of v18
# baseline (speedup 1.0000x reference)
.LBB0_681:
	v_add3_u32 v1, s21, v209, v213
	ds_read_b128 v[6:9], v1
	ds_read_b128 v[10:13], v1 offset:32
	ds_read_b128 v[112:115], v1 offset:64
	ds_read_b128 v[2:5], v1 offset:96
	s_mulk_i32 s31, 0x4800
	v_add_u32_e32 v132, s31, v223
	ds_read_b128 v[124:127], v132 offset:18496
	ds_read_b128 v[128:131], v132 offset:18528
	ds_read_b128 v[134:137], v132 offset:23104
	ds_read_b128 v[138:141], v132 offset:23136
	ds_read_b128 v[142:145], v132 offset:27712
	ds_read_b128 v[146:149], v132 offset:27744
	ds_read_b128 v[150:153], v132 offset:32320
	ds_read_b128 v[154:157], v132 offset:32352
	s_waitcnt lgkmcnt(11)
	v_mfma_f32_32x32x16_bf16 v[96:111], v[6:9], v[176:179], v[160:175]
	v_exp_f32_e32 v7, v16
	v_exp_f32_e32 v9, v17
	v_max_f32_e32 v1, v16, v17
	s_waitcnt lgkmcnt(10)
	v_mfma_f32_32x32x16_bf16 v[96:111], v[10:13], v[180:183], v[96:111]
	v_exp_f32_e32 v11, v18
	v_exp_f32_e32 v12, v19
	v_exp_f32_e32 v13, v20
	v_add_f32_e32 v8, v9, v7
	v_exp_f32_e32 v14, v21
	v_add_f32_e32 v8, v11, v8
	v_exp_f32_e32 v15, v22
	v_max3_f32 v1, v1, v18, v19
	v_add_f32_e32 v8, v12, v8
	v_exp_f32_e32 v16, v23
	v_max3_f32 v1, v1, v20, v21
	v_add_f32_e32 v8, v13, v8
	v_exp_f32_e32 v17, v24
	v_max3_f32 v1, v1, v22, v23
	v_add_f32_e32 v8, v14, v8
	v_exp_f32_e32 v18, v25
	v_max3_f32 v1, v1, v24, v25
	v_add_f32_e32 v8, v15, v8
	v_exp_f32_e32 v19, v26
	v_max3_f32 v1, v1, v26, v27
	v_add_f32_e32 v8, v16, v8
	v_exp_f32_e32 v20, v27
	v_max3_f32 v1, v1, v28, v29
	v_add_f32_e32 v8, v17, v8
	v_exp_f32_e32 v21, v28
	v_max3_f32 v1, v1, v30, v31
	v_mov_b32_e32 v6, v1
	v_add_f32_e32 v8, v18, v8
	v_exp_f32_e32 v22, v29
	v_permlane32_swap_b32_e32 v6, v1
	v_add_f32_e32 v8, v19, v8
	v_exp_f32_e32 v23, v30
	v_add_f32_e32 v8, v20, v8
	v_exp_f32_e32 v24, v31
	v_add_f32_e32 v8, v21, v8
	v_add_f32_e32 v8, v22, v8
	v_add_f32_e32 v8, v23, v8
	v_add_f32_e32 v8, v24, v8
	s_waitcnt lgkmcnt(0)
	v_max_f32_e32 v210, v1, v6
	v_add_f32_e32 v1, v216, v8
	v_cvt_pk_bf16_f32 v8, v21, v22
	v_cvt_pk_bf16_f32 v10, v7, v9
	v_cvt_pk_bf16_f32 v11, v11, v12
	v_cvt_pk_bf16_f32 v12, v13, v14
	v_cvt_pk_bf16_f32 v13, v15, v16
	v_cvt_pk_bf16_f32 v6, v17, v18
	v_cvt_pk_bf16_f32 v7, v19, v20
	v_mfma_f32_32x32x16_bf16 v[96:111], v[112:115], v[184:187], v[96:111]
	v_cvt_pk_bf16_f32 v9, v23, v24
	v_mfma_f32_32x32x16_bf16 v[32:47], v[124:127], v[10:13], v[32:47]
	v_mfma_f32_32x32x16_bf16 v[48:63], v[134:137], v[10:13], v[48:63]
	v_mfma_f32_32x32x16_bf16 v[48:63], v[138:141], v[6:9], v[48:63]
	v_mfma_f32_32x32x16_bf16 v[64:79], v[142:145], v[10:13], v[64:79]
	v_mfma_f32_32x32x16_bf16 v[64:79], v[146:149], v[6:9], v[64:79]
	v_mfma_f32_32x32x16_bf16 v[80:95], v[150:153], v[10:13], v[80:95]
	v_mfma_f32_32x32x16_bf16 v[32:47], v[128:131], v[6:9], v[32:47]
	v_mfma_f32_32x32x16_bf16 v[80:95], v[154:157], v[6:9], v[80:95]
	v_mfma_f32_32x32x16_bf16 v[16:31], v[2:5], v[188:191], v[96:111]
	v_mov_b32_e32 v2, v210
	v_cmp_lt_f32_e32 vcc, s2, v2
	s_cbranch_vccz .LBB0_698
	v_max_f32_e32 v2, v2, v2
	v_max_f32_e32 v3, 0, v2
	v_exp_f32_e64 v2, -v3
	v_add_f32_e32 v6, v217, v3
	v_mul_f32_e32 v1, v2, v1
	s_nop 3
	v_pk_mul_f32 v[46:47], v[46:47], v[2:3] op_sel_hi:[1,0]
	v_pk_mul_f32 v[44:45], v[44:45], v[2:3] op_sel_hi:[1,0]
	v_pk_mul_f32 v[42:43], v[42:43], v[2:3] op_sel_hi:[1,0]
	v_pk_mul_f32 v[40:41], v[40:41], v[2:3] op_sel_hi:[1,0]
	v_pk_mul_f32 v[38:39], v[38:39], v[2:3] op_sel_hi:[1,0]
	v_pk_mul_f32 v[36:37], v[36:37], v[2:3] op_sel_hi:[1,0]
	v_pk_mul_f32 v[34:35], v[34:35], v[2:3] op_sel_hi:[1,0]
	v_pk_mul_f32 v[32:33], v[32:33], v[2:3] op_sel_hi:[1,0]
	v_pk_mul_f32 v[62:63], v[62:63], v[2:3] op_sel_hi:[1,0]
	v_pk_mul_f32 v[60:61], v[60:61], v[2:3] op_sel_hi:[1,0]
	v_pk_mul_f32 v[58:59], v[58:59], v[2:3] op_sel_hi:[1,0]
	v_pk_mul_f32 v[56:57], v[56:57], v[2:3] op_sel_hi:[1,0]
	v_pk_mul_f32 v[54:55], v[54:55], v[2:3] op_sel_hi:[1,0]
	v_pk_mul_f32 v[52:53], v[52:53], v[2:3] op_sel_hi:[1,0]
	v_pk_mul_f32 v[50:51], v[50:51], v[2:3] op_sel_hi:[1,0]
	v_pk_mul_f32 v[48:49], v[48:49], v[2:3] op_sel_hi:[1,0]
	v_pk_mul_f32 v[78:79], v[2:3], v[78:79] op_sel_hi:[0,1]
	v_pk_mul_f32 v[76:77], v[2:3], v[76:77] op_sel_hi:[0,1]
	v_pk_mul_f32 v[74:75], v[2:3], v[74:75] op_sel_hi:[0,1]
	v_pk_mul_f32 v[72:73], v[2:3], v[72:73] op_sel_hi:[0,1]
	v_pk_mul_f32 v[70:71], v[2:3], v[70:71] op_sel_hi:[0,1]
	v_pk_mul_f32 v[68:69], v[2:3], v[68:69] op_sel_hi:[0,1]
	v_pk_mul_f32 v[66:67], v[2:3], v[66:67] op_sel_hi:[0,1]
	v_pk_mul_f32 v[64:65], v[2:3], v[64:65] op_sel_hi:[0,1]
	v_pk_mul_f32 v[94:95], v[2:3], v[94:95] op_sel_hi:[0,1]
	v_pk_mul_f32 v[92:93], v[2:3], v[92:93] op_sel_hi:[0,1]
	v_pk_mul_f32 v[90:91], v[2:3], v[90:91] op_sel_hi:[0,1]
	v_pk_mul_f32 v[88:89], v[2:3], v[88:89] op_sel_hi:[0,1]
	v_pk_mul_f32 v[86:87], v[2:3], v[86:87] op_sel_hi:[0,1]
	v_pk_mul_f32 v[84:85], v[2:3], v[84:85] op_sel_hi:[0,1]
	v_pk_mul_f32 v[82:83], v[2:3], v[82:83] op_sel_hi:[0,1]
	v_pk_mul_f32 v[80:81], v[2:3], v[80:81] op_sel_hi:[0,1]
	v_sub_f32_e32 v16, v16, v3
	v_sub_f32_e32 v17, v17, v3
	v_sub_f32_e32 v18, v18, v3
	v_sub_f32_e32 v19, v19, v3
	v_sub_f32_e32 v20, v20, v3
	v_sub_f32_e32 v21, v21, v3
	v_sub_f32_e32 v22, v22, v3
	v_sub_f32_e32 v23, v23, v3
	v_sub_f32_e32 v24, v24, v3
	v_sub_f32_e32 v25, v25, v3
	v_sub_f32_e32 v26, v26, v3
	v_sub_f32_e32 v27, v27, v3
	v_sub_f32_e32 v28, v28, v3
	v_sub_f32_e32 v29, v29, v3
	v_sub_f32_e32 v30, v30, v3
	v_sub_f32_e32 v31, v31, v3
	v_sub_f32_e32 v160, v160, v3
	v_sub_f32_e32 v161, v161, v3
	v_sub_f32_e32 v162, v162, v3
	v_sub_f32_e32 v163, v163, v3
	v_sub_f32_e32 v164, v164, v3
	v_sub_f32_e32 v165, v165, v3
	v_sub_f32_e32 v166, v166, v3
	v_sub_f32_e32 v167, v167, v3
	v_sub_f32_e32 v168, v168, v3
	v_sub_f32_e32 v169, v169, v3
	v_sub_f32_e32 v170, v170, v3
	v_sub_f32_e32 v171, v171, v3
	v_sub_f32_e32 v172, v172, v3
	v_sub_f32_e32 v173, v173, v3
	v_sub_f32_e32 v174, v174, v3
	v_sub_f32_e32 v175, v175, v3
	s_cbranch_execz .LBB0_685
	s_branch .LBB0_686

.LBB0_694:
	v_add3_u32 v119, s21, v209, v213
	ds_read_b128 v[2:5], v119 offset:4608
	ds_read_b128 v[10:13], v119 offset:4640
	s_mul_i32 s21, s19, 0x4800
	v_add_u32_e32 v132, s21, v223
	ds_read_b128 v[124:127], v132 offset:18432
	ds_read_b128 v[128:131], v132 offset:18464
	ds_read_b128 v[134:137], v132 offset:23040
	ds_read_b128 v[138:141], v132 offset:23072
	ds_read_b128 v[142:145], v132 offset:27648
	ds_read_b128 v[146:149], v132 offset:27680
	ds_read_b128 v[150:153], v132 offset:32256
	ds_read_b128 v[154:157], v132 offset:32288
	s_waitcnt lgkmcnt(9)
	v_mfma_f32_32x32x16_bf16 v[96:111], v[2:5], v[176:179], v[160:175]
	ds_read_b128 v[2:5], v119 offset:4672
	v_exp_f32_e32 v7, v16
	s_waitcnt lgkmcnt(9)
	v_mfma_f32_32x32x16_bf16 v[96:111], v[10:13], v[180:183], v[96:111]
	v_exp_f32_e32 v13, v22
	v_exp_f32_e32 v10, v19
	v_exp_f32_e32 v14, v23
	v_exp_f32_e32 v11, v20
	v_exp_f32_e32 v15, v24
	v_exp_f32_e32 v8, v17
	v_exp_f32_e32 v9, v18
	s_waitcnt lgkmcnt(0)
	v_mfma_f32_32x32x16_bf16 v[96:111], v[2:5], v[184:187], v[96:111]
	v_exp_f32_e32 v113, v26
	v_exp_f32_e32 v114, v27
	v_exp_f32_e32 v115, v28
	v_exp_f32_e32 v12, v21
	v_cvt_pk_bf16_f32 v120, v7, v8
	v_cvt_pk_bf16_f32 v121, v9, v10
	v_cvt_pk_bf16_f32 v123, v13, v14
	v_cvt_pk_bf16_f32 v122, v11, v12
	v_exp_f32_e32 v112, v25
	v_exp_f32_e32 v116, v29
	v_mfma_f32_32x32x16_bf16 v[32:47], v[124:127], v[120:123], v[32:47]
	ds_read_b128 v[124:127], v119 offset:4704
	v_exp_f32_e32 v117, v30
	v_exp_f32_e32 v118, v31
	v_cvt_pk_bf16_f32 v2, v15, v112
	v_cvt_pk_bf16_f32 v3, v113, v114
	v_cvt_pk_bf16_f32 v4, v115, v116
	v_cvt_pk_bf16_f32 v5, v117, v118
	v_max_f32_e32 v16, v16, v17
	v_max3_f32 v16, v16, v18, v19
	v_mfma_f32_32x32x16_bf16 v[32:47], v[128:131], v[2:5], v[32:47]
	v_max3_f32 v16, v16, v20, v21
	v_max3_f32 v16, v16, v22, v23
	v_max3_f32 v20, v16, v24, v25
	v_mfma_f32_32x32x16_bf16 v[48:63], v[134:137], v[120:123], v[48:63]
	v_max3_f32 v20, v20, v26, v27
	v_max3_f32 v20, v20, v28, v29
	v_max3_f32 v20, v20, v30, v31
	v_mov_b32_e32 v21, v20
	s_andn2_b64 vcc, exec, s[92:93]
	v_mfma_f32_32x32x16_bf16 v[48:63], v[138:141], v[2:5], v[48:63]
	v_mfma_f32_32x32x16_bf16 v[64:79], v[142:145], v[120:123], v[64:79]
	v_permlane32_swap_b32_e32 v21, v20
	v_mfma_f32_32x32x16_bf16 v[80:95], v[150:153], v[120:123], v[80:95]
	v_mfma_f32_32x32x16_bf16 v[64:79], v[146:149], v[2:5], v[64:79]
	v_mfma_f32_32x32x16_bf16 v[80:95], v[154:157], v[2:5], v[80:95]
	s_waitcnt lgkmcnt(0)
	v_max_f32_e32 v2, v20, v21
	v_mfma_f32_32x32x16_bf16 v[16:31], v[124:127], v[188:191], v[96:111]
	s_cbranch_vccnz .LBB0_697
	v_cmp_lt_f32_e32 vcc, s2, v2
	s_cbranch_vccz .LBB0_699
	v_max_f32_e32 v2, v2, v2
	v_max_f32_e32 v2, 0, v2
